# P3a SSM full scan hand-written: invariant loads hoisted, next-task prefetch, scalar-FMA recurrence; plus pipelined attention, P2 SSM, P5 epilogue
# speedup vs baseline: 1.0942x; 1.0097x over previous
.Lpa_w1_0:
	s_barrier
	s_cmp_gt_i32 s54, vcc_lo
	s_cbranch_scc0 .Lpa_comp_0
	s_cmp_lt_i32 s54, s29
	s_cbranch_scc0 .Lpa_nv_0s
	s_add_i32 m0, s38, 0x10000
	s_nop 0
	global_load_lds_dwordx4 v166, s[58:59]
	s_add_i32 m0, s57, 0x10000
	s_nop 0
	global_load_lds_dwordx4 v170, s[58:59]
	s_add_u32 s58, s58, 0x10000
	s_addc_u32 s59, s59, 0
.Lpa_nv_0s:
	s_cmp_gt_i32 s54, s53
	s_cbranch_scc1 .Lpa_nk_0s
	s_add_i32 m0, s38, 0x8000
	s_nop 0
	global_load_lds_dwordx4 v166, s[24:25]
	s_add_i32 m0, s57, 0x8000
	s_nop 0
	global_load_lds_dwordx4 v170, s[24:25]
	s_add_u32 s24, s24, 0x10000
	s_addc_u32 s25, s25, 0
.Lpa_nk_0s:
	s_branch .Lpa_next_0
.Lpa_comp_0:
	s_cmp_eq_u32 s54, 1
	s_cbranch_scc0 .Lpa_pend_0
	ds_read_b128 v[96:99], v191 offset:0
	ds_read_b128 v[100:103], v190 offset:0
	ds_read_b128 v[104:107], v189 offset:0
	ds_read_b128 v[108:111], v188 offset:0
	s_waitcnt lgkmcnt(3)
	v_mfma_f32_32x32x16_bf16 v[64:79], v[96:99], v[156:159], 0
	s_waitcnt lgkmcnt(2)
	v_mfma_f32_32x32x16_bf16 v[64:79], v[100:103], v[152:155], v[64:79]
	s_waitcnt lgkmcnt(1)
	v_mfma_f32_32x32x16_bf16 v[64:79], v[104:107], v[148:151], v[64:79]
	s_waitcnt lgkmcnt(0)
	v_mfma_f32_32x32x16_bf16 v[64:79], v[108:111], v[144:147], v[64:79]
	s_cmp_lt_i32 s54, s29
	s_cbranch_scc0 .Lpa_nv_0a
	s_add_i32 m0, s38, 0x10000
	s_nop 0
	global_load_lds_dwordx4 v166, s[58:59]
	s_add_i32 m0, s57, 0x10000
	s_nop 0
	global_load_lds_dwordx4 v170, s[58:59]
	s_add_u32 s58, s58, 0x10000
	s_addc_u32 s59, s59, 0

.Lpa_nk_0a:
	s_nop 11
	v_exp_f32_e32 v64, v64
	v_exp_f32_e32 v65, v65
	v_exp_f32_e32 v66, v66
	v_exp_f32_e32 v67, v67
	v_pk_add_f32 v[198:199], v[198:199], v[64:65]
	v_pk_add_f32 v[200:201], v[200:201], v[66:67]
	v_exp_f32_e32 v68, v68
	v_exp_f32_e32 v69, v69
	v_exp_f32_e32 v70, v70
	v_exp_f32_e32 v71, v71
	v_pk_add_f32 v[198:199], v[198:199], v[68:69]
	v_pk_add_f32 v[200:201], v[200:201], v[70:71]
	v_exp_f32_e32 v72, v72
	v_exp_f32_e32 v73, v73
	v_exp_f32_e32 v74, v74
	v_exp_f32_e32 v75, v75
	v_pk_add_f32 v[198:199], v[198:199], v[72:73]
	v_pk_add_f32 v[200:201], v[200:201], v[74:75]
	v_exp_f32_e32 v76, v76
	v_exp_f32_e32 v77, v77
	v_exp_f32_e32 v78, v78
	v_exp_f32_e32 v79, v79
	v_pk_add_f32 v[198:199], v[198:199], v[76:77]
	v_pk_add_f32 v[200:201], v[200:201], v[78:79]
	v_cvt_pk_bf16_f32 v80, v64, v65
	v_cvt_pk_bf16_f32 v81, v66, v67
	v_cvt_pk_bf16_f32 v82, v68, v69
	v_cvt_pk_bf16_f32 v83, v70, v71
	v_cvt_pk_bf16_f32 v84, v72, v73
	v_cvt_pk_bf16_f32 v85, v74, v75
	v_cvt_pk_bf16_f32 v86, v76, v77
	v_cvt_pk_bf16_f32 v87, v78, v79
	s_branch .Lpa_h1_0
.Lpa_pend_0:
	ds_read_b128 v[96:99], v191 offset:0
	ds_read_b128 v[100:103], v190 offset:0
	ds_read_b128 v[104:107], v189 offset:0
	ds_read_b128 v[108:111], v188 offset:0
	ds_read_b64_tr_b16 v[112:113], v172 offset:40960
	ds_read_b64_tr_b16 v[114:115], v192 offset:40960
	ds_read_b64_tr_b16 v[116:117], v173 offset:40960
	ds_read_b64_tr_b16 v[118:119], v193 offset:40960
	ds_read_b64_tr_b16 v[120:121], v174 offset:40960
	ds_read_b64_tr_b16 v[122:123], v194 offset:40960
	ds_read_b64_tr_b16 v[124:125], v175 offset:40960
	ds_read_b64_tr_b16 v[126:127], v197 offset:40960
	s_waitcnt lgkmcnt(11)
	v_mfma_f32_32x32x16_bf16 v[64:79], v[96:99], v[156:159], 0
	s_waitcnt lgkmcnt(10)
	v_mfma_f32_32x32x16_bf16 v[64:79], v[100:103], v[152:155], v[64:79]
	s_waitcnt lgkmcnt(9)
	v_mfma_f32_32x32x16_bf16 v[64:79], v[104:107], v[148:151], v[64:79]
	s_waitcnt lgkmcnt(8)
	v_mfma_f32_32x32x16_bf16 v[64:79], v[108:111], v[144:147], v[64:79]
	s_waitcnt lgkmcnt(6)
	v_mfma_f32_32x32x16_bf16 v[0:15], v[88:91], v[112:115], v[0:15]
	ds_read_b64_tr_b16 v[112:113], v172 offset:45056
	ds_read_b64_tr_b16 v[114:115], v192 offset:45056
	s_cmp_lt_i32 s54, s29
	s_cbranch_scc0 .Lpa_nv_0b
	s_add_i32 m0, s38, 0x10000
	s_nop 0
	global_load_lds_dwordx4 v166, s[58:59]
	s_add_i32 m0, s57, 0x10000
	s_nop 0
	global_load_lds_dwordx4 v170, s[58:59]
	s_add_u32 s58, s58, 0x10000
	s_addc_u32 s59, s59, 0
.Lpa_nv_0b:
	s_waitcnt lgkmcnt(6)
	v_mfma_f32_32x32x16_bf16 v[16:31], v[88:91], v[116:119], v[16:31]
	ds_read_b64_tr_b16 v[116:117], v173 offset:45056
	ds_read_b64_tr_b16 v[118:119], v193 offset:45056
	s_cmp_gt_i32 s54, s53
	s_cbranch_scc1 .Lpa_nk_0b
	s_add_i32 m0, s38, 0x8000
	s_nop 0
	global_load_lds_dwordx4 v166, s[24:25]
	s_add_i32 m0, s57, 0x8000
	s_nop 0
	global_load_lds_dwordx4 v170, s[24:25]
	s_add_u32 s24, s24, 0x10000
	s_addc_u32 s25, s25, 0
.Lpa_nk_0b:
	s_waitcnt lgkmcnt(6)
	v_mfma_f32_32x32x16_bf16 v[32:47], v[88:91], v[120:123], v[32:47]
	ds_read_b64_tr_b16 v[120:121], v174 offset:45056
	ds_read_b64_tr_b16 v[122:123], v194 offset:45056
	v_exp_f32_e32 v64, v64
	v_exp_f32_e32 v65, v65
	v_exp_f32_e32 v66, v66
	v_exp_f32_e32 v67, v67
	v_pk_add_f32 v[198:199], v[198:199], v[64:65]
	v_pk_add_f32 v[200:201], v[200:201], v[66:67]
	s_waitcnt lgkmcnt(6)
	v_mfma_f32_32x32x16_bf16 v[48:63], v[88:91], v[124:127], v[48:63]
	ds_read_b64_tr_b16 v[124:125], v175 offset:45056
	ds_read_b64_tr_b16 v[126:127], v197 offset:45056
	v_exp_f32_e32 v68, v68
	v_exp_f32_e32 v69, v69
	v_exp_f32_e32 v70, v70
	v_exp_f32_e32 v71, v71
	v_pk_add_f32 v[198:199], v[198:199], v[68:69]
	v_pk_add_f32 v[200:201], v[200:201], v[70:71]
	s_waitcnt lgkmcnt(6)
	v_mfma_f32_32x32x16_bf16 v[0:15], v[92:95], v[112:115], v[0:15]
	v_exp_f32_e32 v72, v72
	v_exp_f32_e32 v73, v73
	v_exp_f32_e32 v74, v74
	v_exp_f32_e32 v75, v75
	v_pk_add_f32 v[198:199], v[198:199], v[72:73]
	v_pk_add_f32 v[200:201], v[200:201], v[74:75]
	s_waitcnt lgkmcnt(4)
	v_mfma_f32_32x32x16_bf16 v[16:31], v[92:95], v[116:119], v[16:31]
	v_exp_f32_e32 v76, v76
	v_exp_f32_e32 v77, v77
	v_exp_f32_e32 v78, v78
	v_exp_f32_e32 v79, v79
	v_pk_add_f32 v[198:199], v[198:199], v[76:77]
	v_pk_add_f32 v[200:201], v[200:201], v[78:79]
	s_waitcnt lgkmcnt(2)
	v_mfma_f32_32x32x16_bf16 v[32:47], v[92:95], v[120:123], v[32:47]
	v_cvt_pk_bf16_f32 v80, v64, v65
	v_cvt_pk_bf16_f32 v81, v66, v67
	v_cvt_pk_bf16_f32 v82, v68, v69
	v_cvt_pk_bf16_f32 v83, v70, v71
	s_waitcnt lgkmcnt(0)
	v_mfma_f32_32x32x16_bf16 v[48:63], v[92:95], v[124:127], v[48:63]
	v_cvt_pk_bf16_f32 v84, v72, v73
	v_cvt_pk_bf16_f32 v85, v74, v75
	v_cvt_pk_bf16_f32 v86, v76, v77
	v_cvt_pk_bf16_f32 v87, v78, v79

.Lpa_w1_1:
	s_barrier
	s_cmp_gt_i32 s54, vcc_lo
	s_cbranch_scc0 .Lpa_comp_1
	s_cmp_lt_i32 s54, s29
	s_cbranch_scc0 .Lpa_nv_1s
	s_add_i32 m0, s38, 0x14000
	s_nop 0
	global_load_lds_dwordx4 v166, s[58:59]
	s_add_i32 m0, s57, 0x14000
	s_nop 0
	global_load_lds_dwordx4 v170, s[58:59]
	s_add_u32 s58, s58, 0x10000
	s_addc_u32 s59, s59, 0
.Lpa_nv_1s:
	s_cmp_gt_i32 s54, s53
	s_cbranch_scc1 .Lpa_nk_1s
	s_add_i32 m0, s38, 0x0
	s_nop 0
	global_load_lds_dwordx4 v166, s[24:25]
	s_add_i32 m0, s57, 0x0
	s_nop 0
	global_load_lds_dwordx4 v170, s[24:25]
	s_add_u32 s24, s24, 0x10000
	s_addc_u32 s25, s25, 0

.Lpa_comp_1:
	ds_read_b128 v[96:99], v191 offset:16384
	ds_read_b128 v[100:103], v190 offset:16384
	ds_read_b128 v[104:107], v189 offset:16384
	ds_read_b128 v[108:111], v188 offset:16384
	ds_read_b64_tr_b16 v[112:113], v172 offset:8192
	ds_read_b64_tr_b16 v[114:115], v192 offset:8192
	ds_read_b64_tr_b16 v[116:117], v173 offset:8192
	ds_read_b64_tr_b16 v[118:119], v193 offset:8192
	ds_read_b64_tr_b16 v[120:121], v174 offset:8192
	ds_read_b64_tr_b16 v[122:123], v194 offset:8192
	ds_read_b64_tr_b16 v[124:125], v175 offset:8192
	ds_read_b64_tr_b16 v[126:127], v197 offset:8192
	s_waitcnt lgkmcnt(11)
	v_mfma_f32_32x32x16_bf16 v[64:79], v[96:99], v[156:159], 0
	s_waitcnt lgkmcnt(10)
	v_mfma_f32_32x32x16_bf16 v[64:79], v[100:103], v[152:155], v[64:79]
	s_waitcnt lgkmcnt(9)
	v_mfma_f32_32x32x16_bf16 v[64:79], v[104:107], v[148:151], v[64:79]
	s_waitcnt lgkmcnt(8)
	v_mfma_f32_32x32x16_bf16 v[64:79], v[108:111], v[144:147], v[64:79]
	s_waitcnt lgkmcnt(6)
	v_mfma_f32_32x32x16_bf16 v[0:15], v[88:91], v[112:115], v[0:15]
	ds_read_b64_tr_b16 v[112:113], v172 offset:12288
	ds_read_b64_tr_b16 v[114:115], v192 offset:12288
	s_cmp_lt_i32 s54, s29
	s_cbranch_scc0 .Lpa_nv_1b
	s_add_i32 m0, s38, 0x14000
	s_nop 0
	global_load_lds_dwordx4 v166, s[58:59]
	s_add_i32 m0, s57, 0x14000
	s_nop 0
	global_load_lds_dwordx4 v170, s[58:59]
	s_add_u32 s58, s58, 0x10000
	s_addc_u32 s59, s59, 0
.Lpa_nv_1b:
	s_waitcnt lgkmcnt(6)
	v_mfma_f32_32x32x16_bf16 v[16:31], v[88:91], v[116:119], v[16:31]
	ds_read_b64_tr_b16 v[116:117], v173 offset:12288
	ds_read_b64_tr_b16 v[118:119], v193 offset:12288
	s_cmp_gt_i32 s54, s53
	s_cbranch_scc1 .Lpa_nk_1b
	s_add_i32 m0, s38, 0x0
	s_nop 0
	global_load_lds_dwordx4 v166, s[24:25]
	s_add_i32 m0, s57, 0x0
	s_nop 0
	global_load_lds_dwordx4 v170, s[24:25]
	s_add_u32 s24, s24, 0x10000
	s_addc_u32 s25, s25, 0
.Lpa_nk_1b:
	s_waitcnt lgkmcnt(6)
	v_mfma_f32_32x32x16_bf16 v[32:47], v[88:91], v[120:123], v[32:47]
	ds_read_b64_tr_b16 v[120:121], v174 offset:12288
	ds_read_b64_tr_b16 v[122:123], v194 offset:12288
	v_exp_f32_e32 v64, v64
	v_exp_f32_e32 v65, v65
	v_exp_f32_e32 v66, v66
	v_exp_f32_e32 v67, v67
	v_pk_add_f32 v[198:199], v[198:199], v[64:65]
	v_pk_add_f32 v[200:201], v[200:201], v[66:67]
	s_waitcnt lgkmcnt(6)
	v_mfma_f32_32x32x16_bf16 v[48:63], v[88:91], v[124:127], v[48:63]
	ds_read_b64_tr_b16 v[124:125], v175 offset:12288
	ds_read_b64_tr_b16 v[126:127], v197 offset:12288
	v_exp_f32_e32 v68, v68
	v_exp_f32_e32 v69, v69
	v_exp_f32_e32 v70, v70
	v_exp_f32_e32 v71, v71
	v_pk_add_f32 v[198:199], v[198:199], v[68:69]
	v_pk_add_f32 v[200:201], v[200:201], v[70:71]
	s_waitcnt lgkmcnt(6)
	v_mfma_f32_32x32x16_bf16 v[0:15], v[92:95], v[112:115], v[0:15]
	v_exp_f32_e32 v72, v72
	v_exp_f32_e32 v73, v73
	v_exp_f32_e32 v74, v74
	v_exp_f32_e32 v75, v75
	v_pk_add_f32 v[198:199], v[198:199], v[72:73]
	v_pk_add_f32 v[200:201], v[200:201], v[74:75]
	s_waitcnt lgkmcnt(4)
	v_mfma_f32_32x32x16_bf16 v[16:31], v[92:95], v[116:119], v[16:31]
	v_exp_f32_e32 v76, v76
	v_exp_f32_e32 v77, v77
	v_exp_f32_e32 v78, v78
	v_exp_f32_e32 v79, v79
	v_pk_add_f32 v[198:199], v[198:199], v[76:77]
	v_pk_add_f32 v[200:201], v[200:201], v[78:79]
	s_waitcnt lgkmcnt(2)
	v_mfma_f32_32x32x16_bf16 v[32:47], v[92:95], v[120:123], v[32:47]
	v_cvt_pk_bf16_f32 v80, v64, v65
	v_cvt_pk_bf16_f32 v81, v66, v67
	v_cvt_pk_bf16_f32 v82, v68, v69
	v_cvt_pk_bf16_f32 v83, v70, v71
	s_waitcnt lgkmcnt(0)
	v_mfma_f32_32x32x16_bf16 v[48:63], v[92:95], v[124:127], v[48:63]
	v_cvt_pk_bf16_f32 v84, v72, v73
	v_cvt_pk_bf16_f32 v85, v74, v75
	v_cvt_pk_bf16_f32 v86, v76, v77
	v_cvt_pk_bf16_f32 v87, v78, v79

.Lpa_w1_2:
	s_barrier
	s_cmp_gt_i32 s54, vcc_lo
	s_cbranch_scc0 .Lpa_comp_2
	s_cmp_lt_i32 s54, s29
	s_cbranch_scc0 .Lpa_nv_2s
	s_add_i32 m0, s38, 0xc000
	s_nop 0
	global_load_lds_dwordx4 v166, s[58:59]
	s_add_i32 m0, s57, 0xc000
	s_nop 0
	global_load_lds_dwordx4 v170, s[58:59]
	s_add_u32 s58, s58, 0x10000
	s_addc_u32 s59, s59, 0
.Lpa_nv_2s:
	s_cmp_gt_i32 s54, s53
	s_cbranch_scc1 .Lpa_nk_2s
	s_add_i32 m0, s38, 0x4000
	s_nop 0
	global_load_lds_dwordx4 v166, s[24:25]
	s_add_i32 m0, s57, 0x4000
	s_nop 0
	global_load_lds_dwordx4 v170, s[24:25]
	s_add_u32 s24, s24, 0x10000
	s_addc_u32 s25, s25, 0

.Lpa_comp_2:
	ds_read_b128 v[96:99], v191 offset:32768
	ds_read_b128 v[100:103], v190 offset:32768
	ds_read_b128 v[104:107], v189 offset:32768
	ds_read_b128 v[108:111], v188 offset:32768
	ds_read_b64_tr_b16 v[112:113], v172 offset:24576
	ds_read_b64_tr_b16 v[114:115], v192 offset:24576
	ds_read_b64_tr_b16 v[116:117], v173 offset:24576
	ds_read_b64_tr_b16 v[118:119], v193 offset:24576
	ds_read_b64_tr_b16 v[120:121], v174 offset:24576
	ds_read_b64_tr_b16 v[122:123], v194 offset:24576
	ds_read_b64_tr_b16 v[124:125], v175 offset:24576
	ds_read_b64_tr_b16 v[126:127], v197 offset:24576
	s_waitcnt lgkmcnt(11)
	v_mfma_f32_32x32x16_bf16 v[64:79], v[96:99], v[156:159], 0
	s_waitcnt lgkmcnt(10)
	v_mfma_f32_32x32x16_bf16 v[64:79], v[100:103], v[152:155], v[64:79]
	s_waitcnt lgkmcnt(9)
	v_mfma_f32_32x32x16_bf16 v[64:79], v[104:107], v[148:151], v[64:79]
	s_waitcnt lgkmcnt(8)
	v_mfma_f32_32x32x16_bf16 v[64:79], v[108:111], v[144:147], v[64:79]
	s_waitcnt lgkmcnt(6)
	v_mfma_f32_32x32x16_bf16 v[0:15], v[88:91], v[112:115], v[0:15]
	ds_read_b64_tr_b16 v[112:113], v172 offset:28672
	ds_read_b64_tr_b16 v[114:115], v192 offset:28672
	s_cmp_lt_i32 s54, s29
	s_cbranch_scc0 .Lpa_nv_2b
	s_add_i32 m0, s38, 0xc000
	s_nop 0
	global_load_lds_dwordx4 v166, s[58:59]
	s_add_i32 m0, s57, 0xc000
	s_nop 0
	global_load_lds_dwordx4 v170, s[58:59]
	s_add_u32 s58, s58, 0x10000
	s_addc_u32 s59, s59, 0
.Lpa_nv_2b:
	s_waitcnt lgkmcnt(6)
	v_mfma_f32_32x32x16_bf16 v[16:31], v[88:91], v[116:119], v[16:31]
	ds_read_b64_tr_b16 v[116:117], v173 offset:28672
	ds_read_b64_tr_b16 v[118:119], v193 offset:28672
	s_cmp_gt_i32 s54, s53
	s_cbranch_scc1 .Lpa_nk_2b
	s_add_i32 m0, s38, 0x4000
	s_nop 0
	global_load_lds_dwordx4 v166, s[24:25]
	s_add_i32 m0, s57, 0x4000
	s_nop 0
	global_load_lds_dwordx4 v170, s[24:25]
	s_add_u32 s24, s24, 0x10000
	s_addc_u32 s25, s25, 0
.Lpa_nk_2b:
	s_waitcnt lgkmcnt(6)
	v_mfma_f32_32x32x16_bf16 v[32:47], v[88:91], v[120:123], v[32:47]
	ds_read_b64_tr_b16 v[120:121], v174 offset:28672
	ds_read_b64_tr_b16 v[122:123], v194 offset:28672
	v_exp_f32_e32 v64, v64
	v_exp_f32_e32 v65, v65
	v_exp_f32_e32 v66, v66
	v_exp_f32_e32 v67, v67
	v_pk_add_f32 v[198:199], v[198:199], v[64:65]
	v_pk_add_f32 v[200:201], v[200:201], v[66:67]
	s_waitcnt lgkmcnt(6)
	v_mfma_f32_32x32x16_bf16 v[48:63], v[88:91], v[124:127], v[48:63]
	ds_read_b64_tr_b16 v[124:125], v175 offset:28672
	ds_read_b64_tr_b16 v[126:127], v197 offset:28672
	v_exp_f32_e32 v68, v68
	v_exp_f32_e32 v69, v69
	v_exp_f32_e32 v70, v70
	v_exp_f32_e32 v71, v71
	v_pk_add_f32 v[198:199], v[198:199], v[68:69]
	v_pk_add_f32 v[200:201], v[200:201], v[70:71]
	s_waitcnt lgkmcnt(6)
	v_mfma_f32_32x32x16_bf16 v[0:15], v[92:95], v[112:115], v[0:15]
	v_exp_f32_e32 v72, v72
	v_exp_f32_e32 v73, v73
	v_exp_f32_e32 v74, v74
	v_exp_f32_e32 v75, v75
	v_pk_add_f32 v[198:199], v[198:199], v[72:73]
	v_pk_add_f32 v[200:201], v[200:201], v[74:75]
	s_waitcnt lgkmcnt(4)
	v_mfma_f32_32x32x16_bf16 v[16:31], v[92:95], v[116:119], v[16:31]
	v_exp_f32_e32 v76, v76
	v_exp_f32_e32 v77, v77
	v_exp_f32_e32 v78, v78
	v_exp_f32_e32 v79, v79
	v_pk_add_f32 v[198:199], v[198:199], v[76:77]
	v_pk_add_f32 v[200:201], v[200:201], v[78:79]
	s_waitcnt lgkmcnt(2)
	v_mfma_f32_32x32x16_bf16 v[32:47], v[92:95], v[120:123], v[32:47]
	v_cvt_pk_bf16_f32 v80, v64, v65
	v_cvt_pk_bf16_f32 v81, v66, v67
	v_cvt_pk_bf16_f32 v82, v68, v69
	v_cvt_pk_bf16_f32 v83, v70, v71
	s_waitcnt lgkmcnt(0)
	v_mfma_f32_32x32x16_bf16 v[48:63], v[92:95], v[124:127], v[48:63]
	v_cvt_pk_bf16_f32 v84, v72, v73
	v_cvt_pk_bf16_f32 v85, v74, v75
	v_cvt_pk_bf16_f32 v86, v76, v77
	v_cvt_pk_bf16_f32 v87, v78, v79

.Lpb_comp_0:
	s_cmp_eq_u32 s54, 1
	s_cbranch_scc0 .Lpb_pend_0
	ds_read_b128 v[96:99], v187 offset:0
	ds_read_b128 v[100:103], v186 offset:0
	ds_read_b128 v[104:107], v185 offset:0
	ds_read_b128 v[108:111], v184 offset:0
	s_waitcnt lgkmcnt(3)
	v_mfma_f32_32x32x16_bf16 v[64:79], v[96:99], v[140:143], 0
	s_waitcnt lgkmcnt(2)
	v_mfma_f32_32x32x16_bf16 v[64:79], v[100:103], v[136:139], v[64:79]
	s_waitcnt lgkmcnt(1)
	v_mfma_f32_32x32x16_bf16 v[64:79], v[104:107], v[132:135], v[64:79]
	s_waitcnt lgkmcnt(0)
	v_mfma_f32_32x32x16_bf16 v[64:79], v[108:111], v[128:131], v[64:79]
	s_cmp_lt_i32 s54, s29
	s_cbranch_scc0 .Lpb_nv_0a
	s_add_i32 m0, s38, 0x10000
	s_nop 0
	global_load_lds_dwordx4 v166, s[58:59]
	s_add_i32 m0, s57, 0x10000
	s_nop 0
	global_load_lds_dwordx4 v170, s[58:59]
	s_add_u32 s58, s58, 0x10000
	s_addc_u32 s59, s59, 0

.Lpb_nk_0a:
	s_nop 11
	v_exp_f32_e32 v64, v64
	v_exp_f32_e32 v65, v65
	v_exp_f32_e32 v66, v66
	v_exp_f32_e32 v67, v67
	v_pk_add_f32 v[188:189], v[188:189], v[64:65]
	v_pk_add_f32 v[190:191], v[190:191], v[66:67]
	v_exp_f32_e32 v68, v68
	v_exp_f32_e32 v69, v69
	v_exp_f32_e32 v70, v70
	v_exp_f32_e32 v71, v71
	v_pk_add_f32 v[188:189], v[188:189], v[68:69]
	v_pk_add_f32 v[190:191], v[190:191], v[70:71]
	v_exp_f32_e32 v72, v72
	v_exp_f32_e32 v73, v73
	v_exp_f32_e32 v74, v74
	v_exp_f32_e32 v75, v75
	v_pk_add_f32 v[188:189], v[188:189], v[72:73]
	v_pk_add_f32 v[190:191], v[190:191], v[74:75]
	v_exp_f32_e32 v76, v76
	v_exp_f32_e32 v77, v77
	v_exp_f32_e32 v78, v78
	v_exp_f32_e32 v79, v79
	v_pk_add_f32 v[188:189], v[188:189], v[76:77]
	v_pk_add_f32 v[190:191], v[190:191], v[78:79]
	v_cvt_pk_bf16_f32 v80, v64, v65
	v_cvt_pk_bf16_f32 v81, v66, v67
	v_cvt_pk_bf16_f32 v82, v68, v69
	v_cvt_pk_bf16_f32 v83, v70, v71
	v_cvt_pk_bf16_f32 v84, v72, v73
	v_cvt_pk_bf16_f32 v85, v74, v75
	v_cvt_pk_bf16_f32 v86, v76, v77
	v_cvt_pk_bf16_f32 v87, v78, v79
	s_branch .Lpb_h1_0
.Lpb_pend_0:
	ds_read_b128 v[96:99], v187 offset:0
	ds_read_b128 v[100:103], v186 offset:0
	ds_read_b128 v[104:107], v185 offset:0
	ds_read_b128 v[108:111], v184 offset:0
	ds_read_b64_tr_b16 v[112:113], v172 offset:40960
	ds_read_b64_tr_b16 v[114:115], v192 offset:40960
	ds_read_b64_tr_b16 v[116:117], v173 offset:40960
	ds_read_b64_tr_b16 v[118:119], v193 offset:40960
	ds_read_b64_tr_b16 v[120:121], v174 offset:40960
	ds_read_b64_tr_b16 v[122:123], v194 offset:40960
	ds_read_b64_tr_b16 v[124:125], v175 offset:40960
	ds_read_b64_tr_b16 v[126:127], v197 offset:40960
	s_waitcnt lgkmcnt(11)
	v_mfma_f32_32x32x16_bf16 v[64:79], v[96:99], v[140:143], 0
	s_waitcnt lgkmcnt(10)
	v_mfma_f32_32x32x16_bf16 v[64:79], v[100:103], v[136:139], v[64:79]
	s_waitcnt lgkmcnt(9)
	v_mfma_f32_32x32x16_bf16 v[64:79], v[104:107], v[132:135], v[64:79]
	s_waitcnt lgkmcnt(8)
	v_mfma_f32_32x32x16_bf16 v[64:79], v[108:111], v[128:131], v[64:79]
	s_waitcnt lgkmcnt(6)
	v_mfma_f32_32x32x16_bf16 v[198:213], v[88:91], v[112:115], v[198:213]
	ds_read_b64_tr_b16 v[112:113], v172 offset:45056
	ds_read_b64_tr_b16 v[114:115], v192 offset:45056
	s_cmp_lt_i32 s54, s29
	s_cbranch_scc0 .Lpb_nv_0b
	s_add_i32 m0, s38, 0x10000
	s_nop 0
	global_load_lds_dwordx4 v166, s[58:59]
	s_add_i32 m0, s57, 0x10000
	s_nop 0
	global_load_lds_dwordx4 v170, s[58:59]
	s_add_u32 s58, s58, 0x10000
	s_addc_u32 s59, s59, 0
.Lpb_nv_0b:
	s_waitcnt lgkmcnt(6)
	v_mfma_f32_32x32x16_bf16 v[214:229], v[88:91], v[116:119], v[214:229]
	ds_read_b64_tr_b16 v[116:117], v173 offset:45056
	ds_read_b64_tr_b16 v[118:119], v193 offset:45056
	s_cmp_gt_i32 s54, s53
	s_cbranch_scc1 .Lpb_nk_0b
	s_add_i32 m0, s38, 0x8000
	s_nop 0
	global_load_lds_dwordx4 v166, s[24:25]
	s_add_i32 m0, s57, 0x8000
	s_nop 0
	global_load_lds_dwordx4 v170, s[24:25]
	s_add_u32 s24, s24, 0x10000
	s_addc_u32 s25, s25, 0
.Lpb_nk_0b:
	s_waitcnt lgkmcnt(6)
	v_mfma_f32_32x32x16_bf16 v[230:245], v[88:91], v[120:123], v[230:245]
	ds_read_b64_tr_b16 v[120:121], v174 offset:45056
	ds_read_b64_tr_b16 v[122:123], v194 offset:45056
	v_exp_f32_e32 v64, v64
	v_exp_f32_e32 v65, v65
	v_exp_f32_e32 v66, v66
	v_exp_f32_e32 v67, v67
	v_pk_add_f32 v[188:189], v[188:189], v[64:65]
	v_pk_add_f32 v[190:191], v[190:191], v[66:67]
	s_waitcnt lgkmcnt(6)
	v_mfma_f32_32x32x16_bf16 v[144:159], v[88:91], v[124:127], v[144:159]
	ds_read_b64_tr_b16 v[124:125], v175 offset:45056
	ds_read_b64_tr_b16 v[126:127], v197 offset:45056
	v_exp_f32_e32 v68, v68
	v_exp_f32_e32 v69, v69
	v_exp_f32_e32 v70, v70
	v_exp_f32_e32 v71, v71
	v_pk_add_f32 v[188:189], v[188:189], v[68:69]
	v_pk_add_f32 v[190:191], v[190:191], v[70:71]
	s_waitcnt lgkmcnt(6)
	v_mfma_f32_32x32x16_bf16 v[198:213], v[92:95], v[112:115], v[198:213]
	v_exp_f32_e32 v72, v72
	v_exp_f32_e32 v73, v73
	v_exp_f32_e32 v74, v74
	v_exp_f32_e32 v75, v75
	v_pk_add_f32 v[188:189], v[188:189], v[72:73]
	v_pk_add_f32 v[190:191], v[190:191], v[74:75]
	s_waitcnt lgkmcnt(4)
	v_mfma_f32_32x32x16_bf16 v[214:229], v[92:95], v[116:119], v[214:229]
	v_exp_f32_e32 v76, v76
	v_exp_f32_e32 v77, v77
	v_exp_f32_e32 v78, v78
	v_exp_f32_e32 v79, v79
	v_pk_add_f32 v[188:189], v[188:189], v[76:77]
	v_pk_add_f32 v[190:191], v[190:191], v[78:79]
	s_waitcnt lgkmcnt(2)
	v_mfma_f32_32x32x16_bf16 v[230:245], v[92:95], v[120:123], v[230:245]
	v_cvt_pk_bf16_f32 v80, v64, v65
	v_cvt_pk_bf16_f32 v81, v66, v67
	v_cvt_pk_bf16_f32 v82, v68, v69
	v_cvt_pk_bf16_f32 v83, v70, v71
	s_waitcnt lgkmcnt(0)
	v_mfma_f32_32x32x16_bf16 v[144:159], v[92:95], v[124:127], v[144:159]
	v_cvt_pk_bf16_f32 v84, v72, v73
	v_cvt_pk_bf16_f32 v85, v74, v75
	v_cvt_pk_bf16_f32 v86, v76, v77
	v_cvt_pk_bf16_f32 v87, v78, v79

.Lpb_comp_1:
	ds_read_b128 v[96:99], v187 offset:16384
	ds_read_b128 v[100:103], v186 offset:16384
	ds_read_b128 v[104:107], v185 offset:16384
	ds_read_b128 v[108:111], v184 offset:16384
	ds_read_b64_tr_b16 v[112:113], v172 offset:8192
	ds_read_b64_tr_b16 v[114:115], v192 offset:8192
	ds_read_b64_tr_b16 v[116:117], v173 offset:8192
	ds_read_b64_tr_b16 v[118:119], v193 offset:8192
	ds_read_b64_tr_b16 v[120:121], v174 offset:8192
	ds_read_b64_tr_b16 v[122:123], v194 offset:8192
	ds_read_b64_tr_b16 v[124:125], v175 offset:8192
	ds_read_b64_tr_b16 v[126:127], v197 offset:8192
	s_waitcnt lgkmcnt(11)
	v_mfma_f32_32x32x16_bf16 v[64:79], v[96:99], v[140:143], 0
	s_waitcnt lgkmcnt(10)
	v_mfma_f32_32x32x16_bf16 v[64:79], v[100:103], v[136:139], v[64:79]
	s_waitcnt lgkmcnt(9)
	v_mfma_f32_32x32x16_bf16 v[64:79], v[104:107], v[132:135], v[64:79]
	s_waitcnt lgkmcnt(8)
	v_mfma_f32_32x32x16_bf16 v[64:79], v[108:111], v[128:131], v[64:79]
	s_waitcnt lgkmcnt(6)
	v_mfma_f32_32x32x16_bf16 v[198:213], v[88:91], v[112:115], v[198:213]
	ds_read_b64_tr_b16 v[112:113], v172 offset:12288
	ds_read_b64_tr_b16 v[114:115], v192 offset:12288
	s_cmp_lt_i32 s54, s29
	s_cbranch_scc0 .Lpb_nv_1b
	s_add_i32 m0, s38, 0x14000
	s_nop 0
	global_load_lds_dwordx4 v166, s[58:59]
	s_add_i32 m0, s57, 0x14000
	s_nop 0
	global_load_lds_dwordx4 v170, s[58:59]
	s_add_u32 s58, s58, 0x10000
	s_addc_u32 s59, s59, 0
.Lpb_nv_1b:
	s_waitcnt lgkmcnt(6)
	v_mfma_f32_32x32x16_bf16 v[214:229], v[88:91], v[116:119], v[214:229]
	ds_read_b64_tr_b16 v[116:117], v173 offset:12288
	ds_read_b64_tr_b16 v[118:119], v193 offset:12288
	s_cmp_gt_i32 s54, s53
	s_cbranch_scc1 .Lpb_nk_1b
	s_add_i32 m0, s38, 0x0
	s_nop 0
	global_load_lds_dwordx4 v166, s[24:25]
	s_add_i32 m0, s57, 0x0
	s_nop 0
	global_load_lds_dwordx4 v170, s[24:25]
	s_add_u32 s24, s24, 0x10000
	s_addc_u32 s25, s25, 0
.Lpb_nk_1b:
	s_waitcnt lgkmcnt(6)
	v_mfma_f32_32x32x16_bf16 v[230:245], v[88:91], v[120:123], v[230:245]
	ds_read_b64_tr_b16 v[120:121], v174 offset:12288
	ds_read_b64_tr_b16 v[122:123], v194 offset:12288
	v_exp_f32_e32 v64, v64
	v_exp_f32_e32 v65, v65
	v_exp_f32_e32 v66, v66
	v_exp_f32_e32 v67, v67
	v_pk_add_f32 v[188:189], v[188:189], v[64:65]
	v_pk_add_f32 v[190:191], v[190:191], v[66:67]
	s_waitcnt lgkmcnt(6)
	v_mfma_f32_32x32x16_bf16 v[144:159], v[88:91], v[124:127], v[144:159]
	ds_read_b64_tr_b16 v[124:125], v175 offset:12288
	ds_read_b64_tr_b16 v[126:127], v197 offset:12288
	v_exp_f32_e32 v68, v68
	v_exp_f32_e32 v69, v69
	v_exp_f32_e32 v70, v70
	v_exp_f32_e32 v71, v71
	v_pk_add_f32 v[188:189], v[188:189], v[68:69]
	v_pk_add_f32 v[190:191], v[190:191], v[70:71]
	s_waitcnt lgkmcnt(6)
	v_mfma_f32_32x32x16_bf16 v[198:213], v[92:95], v[112:115], v[198:213]
	v_exp_f32_e32 v72, v72
	v_exp_f32_e32 v73, v73
	v_exp_f32_e32 v74, v74
	v_exp_f32_e32 v75, v75
	v_pk_add_f32 v[188:189], v[188:189], v[72:73]
	v_pk_add_f32 v[190:191], v[190:191], v[74:75]
	s_waitcnt lgkmcnt(4)
	v_mfma_f32_32x32x16_bf16 v[214:229], v[92:95], v[116:119], v[214:229]
	v_exp_f32_e32 v76, v76
	v_exp_f32_e32 v77, v77
	v_exp_f32_e32 v78, v78
	v_exp_f32_e32 v79, v79
	v_pk_add_f32 v[188:189], v[188:189], v[76:77]
	v_pk_add_f32 v[190:191], v[190:191], v[78:79]
	s_waitcnt lgkmcnt(2)
	v_mfma_f32_32x32x16_bf16 v[230:245], v[92:95], v[120:123], v[230:245]
	v_cvt_pk_bf16_f32 v80, v64, v65
	v_cvt_pk_bf16_f32 v81, v66, v67
	v_cvt_pk_bf16_f32 v82, v68, v69
	v_cvt_pk_bf16_f32 v83, v70, v71
	s_waitcnt lgkmcnt(0)
	v_mfma_f32_32x32x16_bf16 v[144:159], v[92:95], v[124:127], v[144:159]
	v_cvt_pk_bf16_f32 v84, v72, v73
	v_cvt_pk_bf16_f32 v85, v74, v75
	v_cvt_pk_bf16_f32 v86, v76, v77
	v_cvt_pk_bf16_f32 v87, v78, v79

.Lpb_comp_2:
	ds_read_b128 v[96:99], v187 offset:32768
	ds_read_b128 v[100:103], v186 offset:32768
	ds_read_b128 v[104:107], v185 offset:32768
	ds_read_b128 v[108:111], v184 offset:32768
	ds_read_b64_tr_b16 v[112:113], v172 offset:24576
	ds_read_b64_tr_b16 v[114:115], v192 offset:24576
	ds_read_b64_tr_b16 v[116:117], v173 offset:24576
	ds_read_b64_tr_b16 v[118:119], v193 offset:24576
	ds_read_b64_tr_b16 v[120:121], v174 offset:24576
	ds_read_b64_tr_b16 v[122:123], v194 offset:24576
	ds_read_b64_tr_b16 v[124:125], v175 offset:24576
	ds_read_b64_tr_b16 v[126:127], v197 offset:24576
	s_waitcnt lgkmcnt(11)
	v_mfma_f32_32x32x16_bf16 v[64:79], v[96:99], v[140:143], 0
	s_waitcnt lgkmcnt(10)
	v_mfma_f32_32x32x16_bf16 v[64:79], v[100:103], v[136:139], v[64:79]
	s_waitcnt lgkmcnt(9)
	v_mfma_f32_32x32x16_bf16 v[64:79], v[104:107], v[132:135], v[64:79]
	s_waitcnt lgkmcnt(8)
	v_mfma_f32_32x32x16_bf16 v[64:79], v[108:111], v[128:131], v[64:79]
	s_waitcnt lgkmcnt(6)
	v_mfma_f32_32x32x16_bf16 v[198:213], v[88:91], v[112:115], v[198:213]
	ds_read_b64_tr_b16 v[112:113], v172 offset:28672
	ds_read_b64_tr_b16 v[114:115], v192 offset:28672
	s_cmp_lt_i32 s54, s29
	s_cbranch_scc0 .Lpb_nv_2b
	s_add_i32 m0, s38, 0xc000
	s_nop 0
	global_load_lds_dwordx4 v166, s[58:59]
	s_add_i32 m0, s57, 0xc000
	s_nop 0
	global_load_lds_dwordx4 v170, s[58:59]
	s_add_u32 s58, s58, 0x10000
	s_addc_u32 s59, s59, 0
.Lpb_nv_2b:
	s_waitcnt lgkmcnt(6)
	v_mfma_f32_32x32x16_bf16 v[214:229], v[88:91], v[116:119], v[214:229]
	ds_read_b64_tr_b16 v[116:117], v173 offset:28672
	ds_read_b64_tr_b16 v[118:119], v193 offset:28672
	s_cmp_gt_i32 s54, s53
	s_cbranch_scc1 .Lpb_nk_2b
	s_add_i32 m0, s38, 0x4000
	s_nop 0
	global_load_lds_dwordx4 v166, s[24:25]
	s_add_i32 m0, s57, 0x4000
	s_nop 0
	global_load_lds_dwordx4 v170, s[24:25]
	s_add_u32 s24, s24, 0x10000
	s_addc_u32 s25, s25, 0
.Lpb_nk_2b:
	s_waitcnt lgkmcnt(6)
	v_mfma_f32_32x32x16_bf16 v[230:245], v[88:91], v[120:123], v[230:245]
	ds_read_b64_tr_b16 v[120:121], v174 offset:28672
	ds_read_b64_tr_b16 v[122:123], v194 offset:28672
	v_exp_f32_e32 v64, v64
	v_exp_f32_e32 v65, v65
	v_exp_f32_e32 v66, v66
	v_exp_f32_e32 v67, v67
	v_pk_add_f32 v[188:189], v[188:189], v[64:65]
	v_pk_add_f32 v[190:191], v[190:191], v[66:67]
	s_waitcnt lgkmcnt(6)
	v_mfma_f32_32x32x16_bf16 v[144:159], v[88:91], v[124:127], v[144:159]
	ds_read_b64_tr_b16 v[124:125], v175 offset:28672
	ds_read_b64_tr_b16 v[126:127], v197 offset:28672
	v_exp_f32_e32 v68, v68
	v_exp_f32_e32 v69, v69
	v_exp_f32_e32 v70, v70
	v_exp_f32_e32 v71, v71
	v_pk_add_f32 v[188:189], v[188:189], v[68:69]
	v_pk_add_f32 v[190:191], v[190:191], v[70:71]
	s_waitcnt lgkmcnt(6)
	v_mfma_f32_32x32x16_bf16 v[198:213], v[92:95], v[112:115], v[198:213]
	v_exp_f32_e32 v72, v72
	v_exp_f32_e32 v73, v73
	v_exp_f32_e32 v74, v74
	v_exp_f32_e32 v75, v75
	v_pk_add_f32 v[188:189], v[188:189], v[72:73]
	v_pk_add_f32 v[190:191], v[190:191], v[74:75]
	s_waitcnt lgkmcnt(4)
	v_mfma_f32_32x32x16_bf16 v[214:229], v[92:95], v[116:119], v[214:229]
	v_exp_f32_e32 v76, v76
	v_exp_f32_e32 v77, v77
	v_exp_f32_e32 v78, v78
	v_exp_f32_e32 v79, v79
	v_pk_add_f32 v[188:189], v[188:189], v[76:77]
	v_pk_add_f32 v[190:191], v[190:191], v[78:79]
	s_waitcnt lgkmcnt(2)
	v_mfma_f32_32x32x16_bf16 v[230:245], v[92:95], v[120:123], v[230:245]
	v_cvt_pk_bf16_f32 v80, v64, v65
	v_cvt_pk_bf16_f32 v81, v66, v67
	v_cvt_pk_bf16_f32 v82, v68, v69
	v_cvt_pk_bf16_f32 v83, v70, v71
	s_waitcnt lgkmcnt(0)
	v_mfma_f32_32x32x16_bf16 v[144:159], v[92:95], v[124:127], v[144:159]
	v_cvt_pk_bf16_f32 v84, v72, v73
	v_cvt_pk_bf16_f32 v85, v74, v75
	v_cvt_pk_bf16_f32 v86, v76, v77
	v_cvt_pk_bf16_f32 v87, v78, v79

.LBB0_341:
	s_bfe_u32 s4, s86, 0x50006
	s_and_b32 s3, s86, 63
	s_ashr_i32 s24, s86, 11
	s_lshl_b32 s28, s4, 6
	v_or_b32_e32 v0, s28, v160
	v_lshlrev_b32_e32 v0, 2, v0
	global_load_dword v200, v0, s[12:13]
	global_load_dword v201, v0, s[14:15]
	v_lshl_or_b32 v0, s4, 12, v162
	global_load_dwordx4 v[64:67], v0, s[18:19]
	global_load_dwordx4 v[68:71], v0, s[18:19] offset:1024
	global_load_dwordx4 v[72:75], v0, s[18:19] offset:2048
	global_load_dwordx4 v[76:79], v0, s[18:19] offset:3072
	global_load_dwordx4 v[80:83], v0, s[22:23]
	global_load_dwordx4 v[84:87], v0, s[22:23] offset:1024
	global_load_dwordx4 v[88:91], v0, s[22:23] offset:2048
	global_load_dwordx4 v[92:95], v0, s[22:23] offset:3072
	v_lshl_or_b32 v1, v176, 2, s28
	global_load_dword v202, v1, s[16:17]
	v_lshrrev_b32_e32 v2, 5, v160
	v_lshrrev_b32_e32 v3, 4, v160
	v_lshrrev_b32_e32 v4, 1, v160
	v_and_b32_e32 v5, 1, v160
	s_lshl_b32 s25, s24, 12
	s_lshl_b32 s29, s3, 6
	s_or_b32 s25, s25, s29
	s_lshl_b32 s30, s4, 5
	v_add_u32_e32 v6, s25, v164
	v_lshlrev_b32_e32 v6, 10, v6
	v_lshl_add_u32 v6, v2, 4, v6
	v_add_u32_e32 v188, s30, v6
	v_lshl_add_u32 v6, v3, 2, s25
	v_lshlrev_b32_e32 v6, 10, v6
	v_lshl_add_u32 v6, v176, 1, v6
	v_add_u32_e32 v189, s30, v6
	v_add_u32_e32 v6, s25, v4
	v_lshlrev_b32_e32 v6, 10, v6
	v_lshl_add_u32 v6, v5, 4, v6
	v_add_u32_e32 v190, s30, v6
	s_lshl_b32 s29, s24, 11
	s_or_b32 s29, s29, s28
	s_or_b32 s29, s29, s3
	s_lshl_b32 s29, s29, 9
	v_lshl_add_u32 v191, v160, 2, s29
	s_add_u32 s26, s72, 0x2800000
	s_addc_u32 s27, s73, 0
	v_lshl_add_u32 v192, v160, 2, s88
	v_mul_u32_u24_e32 v6, 0x110, v176
	v_lshl_add_u32 v6, v3, 4, v6
	v_add_u32_e32 v193, s88, v6
	v_lshlrev_b32_e32 v6, 7, v3
	v_lshl_add_u32 v6, v176, 1, v6
	v_add_u32_e32 v194, s88, v6
	v_lshl_add_u32 v195, v160, 4, s88
	global_load_dwordx4 v[104:107], v188, s[6:7]
	v_add_u32_e32 v6, 0x8000, v188
	global_load_dwordx4 v[108:111], v6, s[6:7]
	global_load_dword v142, v191, s[26:27]
	global_load_dword v143, v191, s[26:27] offset:256
	s_waitcnt vmcnt(0)
.Lssm3_task:
	s_waitcnt vmcnt(2)
	v_mov_b32_e32 v100, v104
	v_mov_b32_e32 v101, v105
	v_mov_b32_e32 v102, v106
	v_mov_b32_e32 v103, v107
	v_mov_b32_e32 v112, v108
	v_mov_b32_e32 v113, v109
	v_mov_b32_e32 v114, v110
	v_mov_b32_e32 v115, v111
	v_mov_b32_e32 v116, v142
	v_mov_b32_e32 v117, v143
	v_add_u32_e32 v188, 0x400000, v188
	v_add_u32_e32 v191, 0x100000, v191
	v_add_u32_e32 v196, 0x8000, v188
	global_load_dwordx4 v[104:107], v188, s[6:7]
	global_load_dwordx4 v[108:111], v196, s[6:7]
	global_load_dword v142, v191, s[26:27]
	global_load_dword v143, v191, s[26:27] offset:256
	v_add_u32_e32 v197, 0x4000, v189
	v_add_u32_e32 v198, 0x8000, v189
	v_add_u32_e32 v199, 0xc000, v189
	global_load_ushort v124, v189, s[6:7]
	global_load_ushort v125, v189, s[6:7] offset:1024
	global_load_ushort v126, v189, s[6:7] offset:2048
	global_load_ushort v127, v189, s[6:7] offset:3072
	global_load_ushort v128, v197, s[6:7]
	global_load_ushort v129, v197, s[6:7] offset:1024
	global_load_ushort v130, v197, s[6:7] offset:2048
	global_load_ushort v131, v197, s[6:7] offset:3072
	global_load_ushort v132, v198, s[6:7]
	global_load_ushort v133, v198, s[6:7] offset:1024
	global_load_ushort v134, v198, s[6:7] offset:2048
	global_load_ushort v135, v198, s[6:7] offset:3072
	global_load_ushort v136, v199, s[6:7]
	global_load_ushort v137, v199, s[6:7] offset:1024
	global_load_ushort v138, v199, s[6:7] offset:2048
	global_load_ushort v139, v199, s[6:7] offset:3072
	v_mfma_f32_32x32x16_bf16 v[16:31], v[100:103], v[64:67], 0
	v_mfma_f32_32x32x16_bf16 v[32:47], v[100:103], v[68:71], 0
	v_mfma_f32_32x32x16_bf16 v[0:15], v[100:103], v[72:75], 0
	v_mfma_f32_32x32x16_bf16 v[48:63], v[100:103], v[76:79], 0
	s_nop 9
	v_permlane32_swap_b32_e32 v16, v32
	v_permlane32_swap_b32_e32 v17, v33
	v_permlane32_swap_b32_e32 v18, v34
	v_permlane32_swap_b32_e32 v19, v35
	v_permlane32_swap_b32_e32 v20, v36
	v_permlane32_swap_b32_e32 v21, v37
	v_permlane32_swap_b32_e32 v22, v38
	v_permlane32_swap_b32_e32 v23, v39
	v_permlane32_swap_b32_e32 v24, v40
	v_permlane32_swap_b32_e32 v25, v41
	v_permlane32_swap_b32_e32 v26, v42
	v_permlane32_swap_b32_e32 v27, v43
	v_permlane32_swap_b32_e32 v28, v44
	v_permlane32_swap_b32_e32 v29, v45
	v_permlane32_swap_b32_e32 v30, v46
	v_permlane32_swap_b32_e32 v31, v47
	v_permlane32_swap_b32_e32 v0, v48
	v_permlane32_swap_b32_e32 v1, v49
	v_permlane32_swap_b32_e32 v2, v50
	v_permlane32_swap_b32_e32 v3, v51
	v_permlane32_swap_b32_e32 v4, v52
	v_permlane32_swap_b32_e32 v5, v53
	v_permlane32_swap_b32_e32 v6, v54
	v_permlane32_swap_b32_e32 v7, v55
	v_permlane32_swap_b32_e32 v8, v56
	v_permlane32_swap_b32_e32 v9, v57
	v_permlane32_swap_b32_e32 v10, v58
	v_permlane32_swap_b32_e32 v11, v59
	v_permlane32_swap_b32_e32 v12, v60
	v_permlane32_swap_b32_e32 v13, v61
	v_permlane32_swap_b32_e32 v14, v62
	v_permlane32_swap_b32_e32 v15, v63
	v_fma_f32 v118, -v201, v117, v16
	v_fma_f32 v119, v201, v116, v0
	v_fma_f32 v116, v200, v116, v118
	v_fma_f32 v117, v200, v117, v119
	v_cvt_pk_bf16_f32 v120, v116, v117
	ds_write_b32 v192, v120
	v_fma_f32 v118, -v201, v117, v17
	v_fma_f32 v119, v201, v116, v1
	v_fma_f32 v116, v200, v116, v118
	v_fma_f32 v117, v200, v117, v119
	v_cvt_pk_bf16_f32 v121, v116, v117
	ds_write_b32 v192, v121 offset:272
	v_fma_f32 v118, -v201, v117, v18
	v_fma_f32 v119, v201, v116, v2
	v_fma_f32 v116, v200, v116, v118
	v_fma_f32 v117, v200, v117, v119
	v_cvt_pk_bf16_f32 v120, v116, v117
	ds_write_b32 v192, v120 offset:544
	v_fma_f32 v118, -v201, v117, v19
	v_fma_f32 v119, v201, v116, v3
	v_fma_f32 v116, v200, v116, v118
	v_fma_f32 v117, v200, v117, v119
	v_cvt_pk_bf16_f32 v121, v116, v117
	ds_write_b32 v192, v121 offset:816
	v_fma_f32 v118, -v201, v117, v32
	v_fma_f32 v119, v201, v116, v48
	v_fma_f32 v116, v200, v116, v118
	v_fma_f32 v117, v200, v117, v119
	v_cvt_pk_bf16_f32 v120, v116, v117
	ds_write_b32 v192, v120 offset:1088
	v_fma_f32 v118, -v201, v117, v33
	v_fma_f32 v119, v201, v116, v49
	v_fma_f32 v116, v200, v116, v118
	v_fma_f32 v117, v200, v117, v119
	v_cvt_pk_bf16_f32 v121, v116, v117
	ds_write_b32 v192, v121 offset:1360
	v_fma_f32 v118, -v201, v117, v34
	v_fma_f32 v119, v201, v116, v50
	v_fma_f32 v116, v200, v116, v118
	v_fma_f32 v117, v200, v117, v119
	v_cvt_pk_bf16_f32 v120, v116, v117
	ds_write_b32 v192, v120 offset:1632
	v_fma_f32 v118, -v201, v117, v35
	v_fma_f32 v119, v201, v116, v51
	v_fma_f32 v116, v200, v116, v118
	v_fma_f32 v117, v200, v117, v119
	v_cvt_pk_bf16_f32 v121, v116, v117
	ds_write_b32 v192, v121 offset:1904
	v_fma_f32 v118, -v201, v117, v20
	v_fma_f32 v119, v201, v116, v4
	v_fma_f32 v116, v200, v116, v118
	v_fma_f32 v117, v200, v117, v119
	v_cvt_pk_bf16_f32 v120, v116, v117
	ds_write_b32 v192, v120 offset:2176
	v_fma_f32 v118, -v201, v117, v21
	v_fma_f32 v119, v201, v116, v5
	v_fma_f32 v116, v200, v116, v118
	v_fma_f32 v117, v200, v117, v119
	v_cvt_pk_bf16_f32 v121, v116, v117
	ds_write_b32 v192, v121 offset:2448
	v_fma_f32 v118, -v201, v117, v22
	v_fma_f32 v119, v201, v116, v6
	v_fma_f32 v116, v200, v116, v118
	v_fma_f32 v117, v200, v117, v119
	v_cvt_pk_bf16_f32 v120, v116, v117
	ds_write_b32 v192, v120 offset:2720
	v_fma_f32 v118, -v201, v117, v23
	v_fma_f32 v119, v201, v116, v7
	v_fma_f32 v116, v200, v116, v118
	v_fma_f32 v117, v200, v117, v119
	v_cvt_pk_bf16_f32 v121, v116, v117
	ds_write_b32 v192, v121 offset:2992
	v_fma_f32 v118, -v201, v117, v36
	v_fma_f32 v119, v201, v116, v52
	v_fma_f32 v116, v200, v116, v118
	v_fma_f32 v117, v200, v117, v119
	v_cvt_pk_bf16_f32 v120, v116, v117
	ds_write_b32 v192, v120 offset:3264
	v_fma_f32 v118, -v201, v117, v37
	v_fma_f32 v119, v201, v116, v53
	v_fma_f32 v116, v200, v116, v118
	v_fma_f32 v117, v200, v117, v119
	v_cvt_pk_bf16_f32 v121, v116, v117
	ds_write_b32 v192, v121 offset:3536
	v_fma_f32 v118, -v201, v117, v38
	v_fma_f32 v119, v201, v116, v54
	v_fma_f32 v116, v200, v116, v118
	v_fma_f32 v117, v200, v117, v119
	v_cvt_pk_bf16_f32 v120, v116, v117
	ds_write_b32 v192, v120 offset:3808
	v_fma_f32 v118, -v201, v117, v39
	v_fma_f32 v119, v201, v116, v55
	v_fma_f32 v116, v200, v116, v118
	v_fma_f32 v117, v200, v117, v119
	v_cvt_pk_bf16_f32 v121, v116, v117
	ds_write_b32 v192, v121 offset:4080
	v_fma_f32 v118, -v201, v117, v24
	v_fma_f32 v119, v201, v116, v8
	v_fma_f32 v116, v200, v116, v118
	v_fma_f32 v117, v200, v117, v119
	v_cvt_pk_bf16_f32 v120, v116, v117
	ds_write_b32 v192, v120 offset:4352
	v_fma_f32 v118, -v201, v117, v25
	v_fma_f32 v119, v201, v116, v9
	v_fma_f32 v116, v200, v116, v118
	v_fma_f32 v117, v200, v117, v119
	v_cvt_pk_bf16_f32 v121, v116, v117
	ds_write_b32 v192, v121 offset:4624
	v_fma_f32 v118, -v201, v117, v26
	v_fma_f32 v119, v201, v116, v10
	v_fma_f32 v116, v200, v116, v118
	v_fma_f32 v117, v200, v117, v119
	v_cvt_pk_bf16_f32 v120, v116, v117
	ds_write_b32 v192, v120 offset:4896
	v_fma_f32 v118, -v201, v117, v27
	v_fma_f32 v119, v201, v116, v11
	v_fma_f32 v116, v200, v116, v118
	v_fma_f32 v117, v200, v117, v119
	v_cvt_pk_bf16_f32 v121, v116, v117
	ds_write_b32 v192, v121 offset:5168
	v_fma_f32 v118, -v201, v117, v40
	v_fma_f32 v119, v201, v116, v56
	v_fma_f32 v116, v200, v116, v118
	v_fma_f32 v117, v200, v117, v119
	v_cvt_pk_bf16_f32 v120, v116, v117
	ds_write_b32 v192, v120 offset:5440
	v_fma_f32 v118, -v201, v117, v41
	v_fma_f32 v119, v201, v116, v57
	v_fma_f32 v116, v200, v116, v118
	v_fma_f32 v117, v200, v117, v119
	v_cvt_pk_bf16_f32 v121, v116, v117
	ds_write_b32 v192, v121 offset:5712
	v_fma_f32 v118, -v201, v117, v42
	v_fma_f32 v119, v201, v116, v58
	v_fma_f32 v116, v200, v116, v118
	v_fma_f32 v117, v200, v117, v119
	v_cvt_pk_bf16_f32 v120, v116, v117
	ds_write_b32 v192, v120 offset:5984
	v_fma_f32 v118, -v201, v117, v43
	v_fma_f32 v119, v201, v116, v59
	v_fma_f32 v116, v200, v116, v118
	v_fma_f32 v117, v200, v117, v119
	v_cvt_pk_bf16_f32 v121, v116, v117
	ds_write_b32 v192, v121 offset:6256
	v_fma_f32 v118, -v201, v117, v28
	v_fma_f32 v119, v201, v116, v12
	v_fma_f32 v116, v200, v116, v118
	v_fma_f32 v117, v200, v117, v119
	v_cvt_pk_bf16_f32 v120, v116, v117
	ds_write_b32 v192, v120 offset:6528
	v_fma_f32 v118, -v201, v117, v29
	v_fma_f32 v119, v201, v116, v13
	v_fma_f32 v116, v200, v116, v118
	v_fma_f32 v117, v200, v117, v119
	v_cvt_pk_bf16_f32 v121, v116, v117
	ds_write_b32 v192, v121 offset:6800
	v_fma_f32 v118, -v201, v117, v30
	v_fma_f32 v119, v201, v116, v14
	v_fma_f32 v116, v200, v116, v118
	v_fma_f32 v117, v200, v117, v119
	v_cvt_pk_bf16_f32 v120, v116, v117
	ds_write_b32 v192, v120 offset:7072
	v_fma_f32 v118, -v201, v117, v31
	v_fma_f32 v119, v201, v116, v15
	v_fma_f32 v116, v200, v116, v118
	v_fma_f32 v117, v200, v117, v119
	v_cvt_pk_bf16_f32 v121, v116, v117
	ds_write_b32 v192, v121 offset:7344
	v_fma_f32 v118, -v201, v117, v44
	v_fma_f32 v119, v201, v116, v60
	v_fma_f32 v116, v200, v116, v118
	v_fma_f32 v117, v200, v117, v119
	v_cvt_pk_bf16_f32 v120, v116, v117
	ds_write_b32 v192, v120 offset:7616
	v_fma_f32 v118, -v201, v117, v45
	v_fma_f32 v119, v201, v116, v61
	v_fma_f32 v116, v200, v116, v118
	v_fma_f32 v117, v200, v117, v119
	v_cvt_pk_bf16_f32 v121, v116, v117
	ds_write_b32 v192, v121 offset:7888
	v_fma_f32 v118, -v201, v117, v46
	v_fma_f32 v119, v201, v116, v62
	v_fma_f32 v116, v200, v116, v118
	v_fma_f32 v117, v200, v117, v119
	v_cvt_pk_bf16_f32 v120, v116, v117
	ds_write_b32 v192, v120 offset:8160
	v_fma_f32 v118, -v201, v117, v47
	v_fma_f32 v119, v201, v116, v63
	v_fma_f32 v116, v200, v116, v118
	v_fma_f32 v117, v200, v117, v119
	v_cvt_pk_bf16_f32 v121, v116, v117
	ds_write_b32 v192, v121 offset:8432
	ds_read_b128 v[210:213], v193
	ds_read_b128 v[214:217], v193 offset:64
	ds_read_b128 v[218:221], v193 offset:128
	ds_read_b128 v[222:225], v193 offset:192
	ds_read_b128 v[226:229], v193 offset:4352
	ds_read_b128 v[230:233], v193 offset:4416
	ds_read_b128 v[234:237], v193 offset:4480
	ds_read_b128 v[238:241], v193 offset:4544
	s_waitcnt lgkmcnt(7)
	v_mfma_f32_16x16x32_bf16 v[176:179], v[210:213], v[80:83], 0
	s_waitcnt lgkmcnt(6)
	v_mfma_f32_16x16x32_bf16 v[176:179], v[214:217], v[84:87], v[176:179]
	s_waitcnt lgkmcnt(5)
	v_mfma_f32_16x16x32_bf16 v[176:179], v[218:221], v[88:91], v[176:179]
	s_waitcnt lgkmcnt(4)
	v_mfma_f32_16x16x32_bf16 v[176:179], v[222:225], v[92:95], v[176:179]
	s_waitcnt lgkmcnt(3)
	v_mfma_f32_16x16x32_bf16 v[180:183], v[226:229], v[80:83], 0
	s_waitcnt lgkmcnt(2)
	v_mfma_f32_16x16x32_bf16 v[180:183], v[230:233], v[84:87], v[180:183]
	s_waitcnt lgkmcnt(1)
	v_mfma_f32_16x16x32_bf16 v[180:183], v[234:237], v[88:91], v[180:183]
	s_waitcnt lgkmcnt(0)
	v_mfma_f32_16x16x32_bf16 v[180:183], v[238:241], v[92:95], v[180:183]
	s_waitcnt vmcnt(8)
	v_lshlrev_b32_e32 v205, 16, v124
	v_fma_f32 v204, v202, v205, v176
	v_mul_f32_e32 v205, 0x3d372713, v204
	v_mul_f32_e32 v205, v205, v204
	v_fma_f32 v206, v205, v204, v204
	v_mul_f32_e32 v206, 0xc0135761, v206
	v_exp_f32_e32 v207, v206
	s_nop 0
	v_add_f32_e32 v207, 1.0, v207
	v_rcp_f32_e32 v207, v207
	s_nop 0
	v_mul_f32_e32 v204, v204, v207
	v_cvt_pk_bf16_f32 v208, v204, v204
	ds_write_b16 v194, v208
	v_lshlrev_b32_e32 v205, 16, v125
	v_fma_f32 v204, v202, v205, v177
	v_mul_f32_e32 v205, 0x3d372713, v204
	v_mul_f32_e32 v205, v205, v204
	v_fma_f32 v206, v205, v204, v204
	v_mul_f32_e32 v206, 0xc0135761, v206
	v_exp_f32_e32 v207, v206
	s_nop 0
	v_add_f32_e32 v207, 1.0, v207
	v_rcp_f32_e32 v207, v207
	s_nop 0
	v_mul_f32_e32 v204, v204, v207
	v_cvt_pk_bf16_f32 v209, v204, v204
	ds_write_b16 v194, v209 offset:32
	v_lshlrev_b32_e32 v205, 16, v126
	v_fma_f32 v204, v202, v205, v178
	v_mul_f32_e32 v205, 0x3d372713, v204
	v_mul_f32_e32 v205, v205, v204
	v_fma_f32 v206, v205, v204, v204
	v_mul_f32_e32 v206, 0xc0135761, v206
	v_exp_f32_e32 v207, v206
	s_nop 0
	v_add_f32_e32 v207, 1.0, v207
	v_rcp_f32_e32 v207, v207
	s_nop 0
	v_mul_f32_e32 v204, v204, v207
	v_cvt_pk_bf16_f32 v208, v204, v204
	ds_write_b16 v194, v208 offset:64
	v_lshlrev_b32_e32 v205, 16, v127
	v_fma_f32 v204, v202, v205, v179
	v_mul_f32_e32 v205, 0x3d372713, v204
	v_mul_f32_e32 v205, v205, v204
	v_fma_f32 v206, v205, v204, v204
	v_mul_f32_e32 v206, 0xc0135761, v206
	v_exp_f32_e32 v207, v206
	s_nop 0
	v_add_f32_e32 v207, 1.0, v207
	v_rcp_f32_e32 v207, v207
	s_nop 0
	v_mul_f32_e32 v204, v204, v207
	v_cvt_pk_bf16_f32 v209, v204, v204
	ds_write_b16 v194, v209 offset:96
	v_lshlrev_b32_e32 v205, 16, v128
	v_fma_f32 v204, v202, v205, v180
	v_mul_f32_e32 v205, 0x3d372713, v204
	v_mul_f32_e32 v205, v205, v204
	v_fma_f32 v206, v205, v204, v204
	v_mul_f32_e32 v206, 0xc0135761, v206
	v_exp_f32_e32 v207, v206
	s_nop 0
	v_add_f32_e32 v207, 1.0, v207
	v_rcp_f32_e32 v207, v207
	s_nop 0
	v_mul_f32_e32 v204, v204, v207
	v_cvt_pk_bf16_f32 v208, v204, v204
	ds_write_b16 v194, v208 offset:512
	v_lshlrev_b32_e32 v205, 16, v129
	v_fma_f32 v204, v202, v205, v181
	v_mul_f32_e32 v205, 0x3d372713, v204
	v_mul_f32_e32 v205, v205, v204
	v_fma_f32 v206, v205, v204, v204
	v_mul_f32_e32 v206, 0xc0135761, v206
	v_exp_f32_e32 v207, v206
	s_nop 0
	v_add_f32_e32 v207, 1.0, v207
	v_rcp_f32_e32 v207, v207
	s_nop 0
	v_mul_f32_e32 v204, v204, v207
	v_cvt_pk_bf16_f32 v209, v204, v204
	ds_write_b16 v194, v209 offset:544
	v_lshlrev_b32_e32 v205, 16, v130
	v_fma_f32 v204, v202, v205, v182
	v_mul_f32_e32 v205, 0x3d372713, v204
	v_mul_f32_e32 v205, v205, v204
	v_fma_f32 v206, v205, v204, v204
	v_mul_f32_e32 v206, 0xc0135761, v206
	v_exp_f32_e32 v207, v206
	s_nop 0
	v_add_f32_e32 v207, 1.0, v207
	v_rcp_f32_e32 v207, v207
	s_nop 0
	v_mul_f32_e32 v204, v204, v207
	v_cvt_pk_bf16_f32 v208, v204, v204
	ds_write_b16 v194, v208 offset:576
	v_lshlrev_b32_e32 v205, 16, v131
	v_fma_f32 v204, v202, v205, v183
	v_mul_f32_e32 v205, 0x3d372713, v204
	v_mul_f32_e32 v205, v205, v204
	v_fma_f32 v206, v205, v204, v204
	v_mul_f32_e32 v206, 0xc0135761, v206
	v_exp_f32_e32 v207, v206
	s_nop 0
	v_add_f32_e32 v207, 1.0, v207
	v_rcp_f32_e32 v207, v207
	s_nop 0
	v_mul_f32_e32 v204, v204, v207
	v_cvt_pk_bf16_f32 v209, v204, v204
	ds_write_b16 v194, v209 offset:608
	ds_read_b128 v[184:187], v195
	s_waitcnt lgkmcnt(0)
	global_store_dwordx4 v190, v[184:187], s[6:7]
	v_mfma_f32_32x32x16_bf16 v[16:31], v[112:115], v[64:67], 0
	v_mfma_f32_32x32x16_bf16 v[32:47], v[112:115], v[68:71], 0
	v_mfma_f32_32x32x16_bf16 v[0:15], v[112:115], v[72:75], 0
	v_mfma_f32_32x32x16_bf16 v[48:63], v[112:115], v[76:79], 0
	s_nop 9
	v_permlane32_swap_b32_e32 v16, v32
	v_permlane32_swap_b32_e32 v17, v33
	v_permlane32_swap_b32_e32 v18, v34
	v_permlane32_swap_b32_e32 v19, v35
	v_permlane32_swap_b32_e32 v20, v36
	v_permlane32_swap_b32_e32 v21, v37
	v_permlane32_swap_b32_e32 v22, v38
	v_permlane32_swap_b32_e32 v23, v39
	v_permlane32_swap_b32_e32 v24, v40
	v_permlane32_swap_b32_e32 v25, v41
	v_permlane32_swap_b32_e32 v26, v42
	v_permlane32_swap_b32_e32 v27, v43
	v_permlane32_swap_b32_e32 v28, v44
	v_permlane32_swap_b32_e32 v29, v45
	v_permlane32_swap_b32_e32 v30, v46
	v_permlane32_swap_b32_e32 v31, v47
	v_permlane32_swap_b32_e32 v0, v48
	v_permlane32_swap_b32_e32 v1, v49
	v_permlane32_swap_b32_e32 v2, v50
	v_permlane32_swap_b32_e32 v3, v51
	v_permlane32_swap_b32_e32 v4, v52
	v_permlane32_swap_b32_e32 v5, v53
	v_permlane32_swap_b32_e32 v6, v54
	v_permlane32_swap_b32_e32 v7, v55
	v_permlane32_swap_b32_e32 v8, v56
	v_permlane32_swap_b32_e32 v9, v57
	v_permlane32_swap_b32_e32 v10, v58
	v_permlane32_swap_b32_e32 v11, v59
	v_permlane32_swap_b32_e32 v12, v60
	v_permlane32_swap_b32_e32 v13, v61
	v_permlane32_swap_b32_e32 v14, v62
	v_permlane32_swap_b32_e32 v15, v63
	v_fma_f32 v118, -v201, v117, v16
	v_fma_f32 v119, v201, v116, v0
	v_fma_f32 v116, v200, v116, v118
	v_fma_f32 v117, v200, v117, v119
	v_cvt_pk_bf16_f32 v120, v116, v117
	ds_write_b32 v192, v120
	v_fma_f32 v118, -v201, v117, v17
	v_fma_f32 v119, v201, v116, v1
	v_fma_f32 v116, v200, v116, v118
	v_fma_f32 v117, v200, v117, v119
	v_cvt_pk_bf16_f32 v121, v116, v117
	ds_write_b32 v192, v121 offset:272
	v_fma_f32 v118, -v201, v117, v18
	v_fma_f32 v119, v201, v116, v2
	v_fma_f32 v116, v200, v116, v118
	v_fma_f32 v117, v200, v117, v119
	v_cvt_pk_bf16_f32 v120, v116, v117
	ds_write_b32 v192, v120 offset:544
	v_fma_f32 v118, -v201, v117, v19
	v_fma_f32 v119, v201, v116, v3
	v_fma_f32 v116, v200, v116, v118
	v_fma_f32 v117, v200, v117, v119
	v_cvt_pk_bf16_f32 v121, v116, v117
	ds_write_b32 v192, v121 offset:816
	v_fma_f32 v118, -v201, v117, v32
	v_fma_f32 v119, v201, v116, v48
	v_fma_f32 v116, v200, v116, v118
	v_fma_f32 v117, v200, v117, v119
	v_cvt_pk_bf16_f32 v120, v116, v117
	ds_write_b32 v192, v120 offset:1088
	v_fma_f32 v118, -v201, v117, v33
	v_fma_f32 v119, v201, v116, v49
	v_fma_f32 v116, v200, v116, v118
	v_fma_f32 v117, v200, v117, v119
	v_cvt_pk_bf16_f32 v121, v116, v117
	ds_write_b32 v192, v121 offset:1360
	v_fma_f32 v118, -v201, v117, v34
	v_fma_f32 v119, v201, v116, v50
	v_fma_f32 v116, v200, v116, v118
	v_fma_f32 v117, v200, v117, v119
	v_cvt_pk_bf16_f32 v120, v116, v117
	ds_write_b32 v192, v120 offset:1632
	v_fma_f32 v118, -v201, v117, v35
	v_fma_f32 v119, v201, v116, v51
	v_fma_f32 v116, v200, v116, v118
	v_fma_f32 v117, v200, v117, v119
	v_cvt_pk_bf16_f32 v121, v116, v117
	ds_write_b32 v192, v121 offset:1904
	v_fma_f32 v118, -v201, v117, v20
	v_fma_f32 v119, v201, v116, v4
	v_fma_f32 v116, v200, v116, v118
	v_fma_f32 v117, v200, v117, v119
	v_cvt_pk_bf16_f32 v120, v116, v117
	ds_write_b32 v192, v120 offset:2176
	v_fma_f32 v118, -v201, v117, v21
	v_fma_f32 v119, v201, v116, v5
	v_fma_f32 v116, v200, v116, v118
	v_fma_f32 v117, v200, v117, v119
	v_cvt_pk_bf16_f32 v121, v116, v117
	ds_write_b32 v192, v121 offset:2448
	v_fma_f32 v118, -v201, v117, v22
	v_fma_f32 v119, v201, v116, v6
	v_fma_f32 v116, v200, v116, v118
	v_fma_f32 v117, v200, v117, v119
	v_cvt_pk_bf16_f32 v120, v116, v117
	ds_write_b32 v192, v120 offset:2720
	v_fma_f32 v118, -v201, v117, v23
	v_fma_f32 v119, v201, v116, v7
	v_fma_f32 v116, v200, v116, v118
	v_fma_f32 v117, v200, v117, v119
	v_cvt_pk_bf16_f32 v121, v116, v117
	ds_write_b32 v192, v121 offset:2992
	v_fma_f32 v118, -v201, v117, v36
	v_fma_f32 v119, v201, v116, v52
	v_fma_f32 v116, v200, v116, v118
	v_fma_f32 v117, v200, v117, v119
	v_cvt_pk_bf16_f32 v120, v116, v117
	ds_write_b32 v192, v120 offset:3264
	v_fma_f32 v118, -v201, v117, v37
	v_fma_f32 v119, v201, v116, v53
	v_fma_f32 v116, v200, v116, v118
	v_fma_f32 v117, v200, v117, v119
	v_cvt_pk_bf16_f32 v121, v116, v117
	ds_write_b32 v192, v121 offset:3536
	v_fma_f32 v118, -v201, v117, v38
	v_fma_f32 v119, v201, v116, v54
	v_fma_f32 v116, v200, v116, v118
	v_fma_f32 v117, v200, v117, v119
	v_cvt_pk_bf16_f32 v120, v116, v117
	ds_write_b32 v192, v120 offset:3808
	v_fma_f32 v118, -v201, v117, v39
	v_fma_f32 v119, v201, v116, v55
	v_fma_f32 v116, v200, v116, v118
	v_fma_f32 v117, v200, v117, v119
	v_cvt_pk_bf16_f32 v121, v116, v117
	ds_write_b32 v192, v121 offset:4080
	v_fma_f32 v118, -v201, v117, v24
	v_fma_f32 v119, v201, v116, v8
	v_fma_f32 v116, v200, v116, v118
	v_fma_f32 v117, v200, v117, v119
	v_cvt_pk_bf16_f32 v120, v116, v117
	ds_write_b32 v192, v120 offset:4352
	v_fma_f32 v118, -v201, v117, v25
	v_fma_f32 v119, v201, v116, v9
	v_fma_f32 v116, v200, v116, v118
	v_fma_f32 v117, v200, v117, v119
	v_cvt_pk_bf16_f32 v121, v116, v117
	ds_write_b32 v192, v121 offset:4624
	v_fma_f32 v118, -v201, v117, v26
	v_fma_f32 v119, v201, v116, v10
	v_fma_f32 v116, v200, v116, v118
	v_fma_f32 v117, v200, v117, v119
	v_cvt_pk_bf16_f32 v120, v116, v117
	ds_write_b32 v192, v120 offset:4896
	v_fma_f32 v118, -v201, v117, v27
	v_fma_f32 v119, v201, v116, v11
	v_fma_f32 v116, v200, v116, v118
	v_fma_f32 v117, v200, v117, v119
	v_cvt_pk_bf16_f32 v121, v116, v117
	ds_write_b32 v192, v121 offset:5168
	v_fma_f32 v118, -v201, v117, v40
	v_fma_f32 v119, v201, v116, v56
	v_fma_f32 v116, v200, v116, v118
	v_fma_f32 v117, v200, v117, v119
	v_cvt_pk_bf16_f32 v120, v116, v117
	ds_write_b32 v192, v120 offset:5440
	v_fma_f32 v118, -v201, v117, v41
	v_fma_f32 v119, v201, v116, v57
	v_fma_f32 v116, v200, v116, v118
	v_fma_f32 v117, v200, v117, v119
	v_cvt_pk_bf16_f32 v121, v116, v117
	ds_write_b32 v192, v121 offset:5712
	v_fma_f32 v118, -v201, v117, v42
	v_fma_f32 v119, v201, v116, v58
	v_fma_f32 v116, v200, v116, v118
	v_fma_f32 v117, v200, v117, v119
	v_cvt_pk_bf16_f32 v120, v116, v117
	ds_write_b32 v192, v120 offset:5984
	v_fma_f32 v118, -v201, v117, v43
	v_fma_f32 v119, v201, v116, v59
	v_fma_f32 v116, v200, v116, v118
	v_fma_f32 v117, v200, v117, v119
	v_cvt_pk_bf16_f32 v121, v116, v117
	ds_write_b32 v192, v121 offset:6256
	v_fma_f32 v118, -v201, v117, v28
	v_fma_f32 v119, v201, v116, v12
	v_fma_f32 v116, v200, v116, v118
	v_fma_f32 v117, v200, v117, v119
	v_cvt_pk_bf16_f32 v120, v116, v117
	ds_write_b32 v192, v120 offset:6528
	v_fma_f32 v118, -v201, v117, v29
	v_fma_f32 v119, v201, v116, v13
	v_fma_f32 v116, v200, v116, v118
	v_fma_f32 v117, v200, v117, v119
	v_cvt_pk_bf16_f32 v121, v116, v117
	ds_write_b32 v192, v121 offset:6800
	v_fma_f32 v118, -v201, v117, v30
	v_fma_f32 v119, v201, v116, v14
	v_fma_f32 v116, v200, v116, v118
	v_fma_f32 v117, v200, v117, v119
	v_cvt_pk_bf16_f32 v120, v116, v117
	ds_write_b32 v192, v120 offset:7072
	v_fma_f32 v118, -v201, v117, v31
	v_fma_f32 v119, v201, v116, v15
	v_fma_f32 v116, v200, v116, v118
	v_fma_f32 v117, v200, v117, v119
	v_cvt_pk_bf16_f32 v121, v116, v117
	ds_write_b32 v192, v121 offset:7344
	v_fma_f32 v118, -v201, v117, v44
	v_fma_f32 v119, v201, v116, v60
	v_fma_f32 v116, v200, v116, v118
	v_fma_f32 v117, v200, v117, v119
	v_cvt_pk_bf16_f32 v120, v116, v117
	ds_write_b32 v192, v120 offset:7616
	v_fma_f32 v118, -v201, v117, v45
	v_fma_f32 v119, v201, v116, v61
	v_fma_f32 v116, v200, v116, v118
	v_fma_f32 v117, v200, v117, v119
	v_cvt_pk_bf16_f32 v121, v116, v117
	ds_write_b32 v192, v121 offset:7888
	v_fma_f32 v118, -v201, v117, v46
	v_fma_f32 v119, v201, v116, v62
	v_fma_f32 v116, v200, v116, v118
	v_fma_f32 v117, v200, v117, v119
	v_cvt_pk_bf16_f32 v120, v116, v117
	ds_write_b32 v192, v120 offset:8160
	v_fma_f32 v118, -v201, v117, v47
	v_fma_f32 v119, v201, v116, v63
	v_fma_f32 v116, v200, v116, v118
	v_fma_f32 v117, v200, v117, v119
	v_cvt_pk_bf16_f32 v121, v116, v117
	ds_write_b32 v192, v121 offset:8432
	ds_read_b128 v[210:213], v193
	ds_read_b128 v[214:217], v193 offset:64
	ds_read_b128 v[218:221], v193 offset:128
	ds_read_b128 v[222:225], v193 offset:192
	ds_read_b128 v[226:229], v193 offset:4352
	ds_read_b128 v[230:233], v193 offset:4416
	ds_read_b128 v[234:237], v193 offset:4480
	ds_read_b128 v[238:241], v193 offset:4544
	s_waitcnt lgkmcnt(7)
	v_mfma_f32_16x16x32_bf16 v[176:179], v[210:213], v[80:83], 0
	s_waitcnt lgkmcnt(6)
	v_mfma_f32_16x16x32_bf16 v[176:179], v[214:217], v[84:87], v[176:179]
	s_waitcnt lgkmcnt(5)
	v_mfma_f32_16x16x32_bf16 v[176:179], v[218:221], v[88:91], v[176:179]
	s_waitcnt lgkmcnt(4)
	v_mfma_f32_16x16x32_bf16 v[176:179], v[222:225], v[92:95], v[176:179]
	s_waitcnt lgkmcnt(3)
	v_mfma_f32_16x16x32_bf16 v[180:183], v[226:229], v[80:83], 0
	s_waitcnt lgkmcnt(2)
	v_mfma_f32_16x16x32_bf16 v[180:183], v[230:233], v[84:87], v[180:183]
	s_waitcnt lgkmcnt(1)
	v_mfma_f32_16x16x32_bf16 v[180:183], v[234:237], v[88:91], v[180:183]
	s_waitcnt lgkmcnt(0)
	v_mfma_f32_16x16x32_bf16 v[180:183], v[238:241], v[92:95], v[180:183]
	s_waitcnt vmcnt(1)
	v_lshlrev_b32_e32 v205, 16, v132
	v_fma_f32 v204, v202, v205, v176
	v_mul_f32_e32 v205, 0x3d372713, v204
	v_mul_f32_e32 v205, v205, v204
	v_fma_f32 v206, v205, v204, v204
	v_mul_f32_e32 v206, 0xc0135761, v206
	v_exp_f32_e32 v207, v206
	s_nop 0
	v_add_f32_e32 v207, 1.0, v207
	v_rcp_f32_e32 v207, v207
	s_nop 0
	v_mul_f32_e32 v204, v204, v207
	v_cvt_pk_bf16_f32 v208, v204, v204
	ds_write_b16 v194, v208
	v_lshlrev_b32_e32 v205, 16, v133
	v_fma_f32 v204, v202, v205, v177
	v_mul_f32_e32 v205, 0x3d372713, v204
	v_mul_f32_e32 v205, v205, v204
	v_fma_f32 v206, v205, v204, v204
	v_mul_f32_e32 v206, 0xc0135761, v206
	v_exp_f32_e32 v207, v206
	s_nop 0
	v_add_f32_e32 v207, 1.0, v207
	v_rcp_f32_e32 v207, v207
	s_nop 0
	v_mul_f32_e32 v204, v204, v207
	v_cvt_pk_bf16_f32 v209, v204, v204
	ds_write_b16 v194, v209 offset:32
	v_lshlrev_b32_e32 v205, 16, v134
	v_fma_f32 v204, v202, v205, v178
	v_mul_f32_e32 v205, 0x3d372713, v204
	v_mul_f32_e32 v205, v205, v204
	v_fma_f32 v206, v205, v204, v204
	v_mul_f32_e32 v206, 0xc0135761, v206
	v_exp_f32_e32 v207, v206
	s_nop 0
	v_add_f32_e32 v207, 1.0, v207
	v_rcp_f32_e32 v207, v207
	s_nop 0
	v_mul_f32_e32 v204, v204, v207
	v_cvt_pk_bf16_f32 v208, v204, v204
	ds_write_b16 v194, v208 offset:64
	v_lshlrev_b32_e32 v205, 16, v135
	v_fma_f32 v204, v202, v205, v179
	v_mul_f32_e32 v205, 0x3d372713, v204
	v_mul_f32_e32 v205, v205, v204
	v_fma_f32 v206, v205, v204, v204
	v_mul_f32_e32 v206, 0xc0135761, v206
	v_exp_f32_e32 v207, v206
	s_nop 0
	v_add_f32_e32 v207, 1.0, v207
	v_rcp_f32_e32 v207, v207
	s_nop 0
	v_mul_f32_e32 v204, v204, v207
	v_cvt_pk_bf16_f32 v209, v204, v204
	ds_write_b16 v194, v209 offset:96
	v_lshlrev_b32_e32 v205, 16, v136
	v_fma_f32 v204, v202, v205, v180
	v_mul_f32_e32 v205, 0x3d372713, v204
	v_mul_f32_e32 v205, v205, v204
	v_fma_f32 v206, v205, v204, v204
	v_mul_f32_e32 v206, 0xc0135761, v206
	v_exp_f32_e32 v207, v206
	s_nop 0
	v_add_f32_e32 v207, 1.0, v207
	v_rcp_f32_e32 v207, v207
	s_nop 0
	v_mul_f32_e32 v204, v204, v207
	v_cvt_pk_bf16_f32 v208, v204, v204
	ds_write_b16 v194, v208 offset:512
	v_lshlrev_b32_e32 v205, 16, v137
	v_fma_f32 v204, v202, v205, v181
	v_mul_f32_e32 v205, 0x3d372713, v204
	v_mul_f32_e32 v205, v205, v204
	v_fma_f32 v206, v205, v204, v204
	v_mul_f32_e32 v206, 0xc0135761, v206
	v_exp_f32_e32 v207, v206
	s_nop 0
	v_add_f32_e32 v207, 1.0, v207
	v_rcp_f32_e32 v207, v207
	s_nop 0
	v_mul_f32_e32 v204, v204, v207
	v_cvt_pk_bf16_f32 v209, v204, v204
	ds_write_b16 v194, v209 offset:544
	v_lshlrev_b32_e32 v205, 16, v138
	v_fma_f32 v204, v202, v205, v182
	v_mul_f32_e32 v205, 0x3d372713, v204
	v_mul_f32_e32 v205, v205, v204
	v_fma_f32 v206, v205, v204, v204
	v_mul_f32_e32 v206, 0xc0135761, v206
	v_exp_f32_e32 v207, v206
	s_nop 0
	v_add_f32_e32 v207, 1.0, v207
	v_rcp_f32_e32 v207, v207
	s_nop 0
	v_mul_f32_e32 v204, v204, v207
	v_cvt_pk_bf16_f32 v208, v204, v204
	ds_write_b16 v194, v208 offset:576
	v_lshlrev_b32_e32 v205, 16, v139
	v_fma_f32 v204, v202, v205, v183
	v_mul_f32_e32 v205, 0x3d372713, v204
	v_mul_f32_e32 v205, v205, v204
	v_fma_f32 v206, v205, v204, v204
	v_mul_f32_e32 v206, 0xc0135761, v206
	v_exp_f32_e32 v207, v206
	s_nop 0
	v_add_f32_e32 v207, 1.0, v207
	v_rcp_f32_e32 v207, v207
	s_nop 0
	v_mul_f32_e32 v204, v204, v207
	v_cvt_pk_bf16_f32 v209, v204, v204
	ds_write_b16 v194, v209 offset:608
	ds_read_b128 v[184:187], v195
	v_add_u32_e32 v196, 0x8000, v190
	s_waitcnt lgkmcnt(0)
	global_store_dwordx4 v196, v[184:187], s[6:7]
	v_add_u32_e32 v189, 0x400000, v189
	v_add_u32_e32 v190, 0x400000, v190
	s_add_i32 s86, s86, s87
	s_cmpk_gt_i32 s86, 0x3fff
	s_cbranch_scc0 .Lssm3_task
